# combo2 + workgroups on XCDs 2,3,6,7 run their GLU-GEMM units before their attention units (S5-count poll only), others after
# baseline (speedup 1.0000x reference)
.LBB0_617:
	s_or_b64 exec, exec, s[4:5]
	v_writelane_b32 v253, s33, 61
	s_add_u32 s42, s22, 0x104000
	v_readlane_b32 s2, v253, 55
	v_readlane_b32 s3, v253, 56
	s_addc_u32 s43, s23, 0
	s_andn2_b64 vcc, exec, s[2:3]
	s_waitcnt lgkmcnt(0)
	s_barrier
	s_bfe_u32 s98, s97, 0x10001
	s_cbranch_vccnz .LBB0_619
	s_lshl_b32 s46, s96, 3
	s_lshl_b32 s93, s96, 5
	s_mov_b32 s47, 0
	s_lshl_b32 s36, s96, 4
	s_and_b32 s44, s46, 0x1fffffe0
	s_lshl_b32 s49, s96, 12
	s_mov_b64 s[4:5], 0
	s_branch .LBB0_620

.LBB0_629:
	s_cmp_lg_u32 s98, 1
	s_cbranch_scc1 .Lmy_att_go
	s_mov_b32 s98, 2
	v_writelane_b32 v252, s19, 2
	v_writelane_b32 v252, s26, 3
	v_writelane_b32 v252, s27, 4
	v_writelane_b32 v252, s28, 5
	v_writelane_b32 v252, s29, 6
	v_writelane_b32 v252, s30, 7
	v_writelane_b32 v252, s31, 8
	v_writelane_b32 v252, s33, 9
	v_writelane_b32 v252, s38, 10
	v_writelane_b32 v252, s42, 11
	v_writelane_b32 v252, s43, 12
	v_writelane_b32 v252, s44, 13
	v_writelane_b32 v252, s46, 14
	v_writelane_b32 v252, s47, 15
	v_writelane_b32 v252, s49, 16
	s_add_u32 s6, s22, 0x16800000
	s_addc_u32 s7, s23, 0
	s_branch .LBB0_695

.LBB0_695:
	s_cmp_lg_u32 s98, 3
	s_cbranch_scc1 .Lmy_p3_go
	v_readlane_b32 s3, v252, 20
	v_readlane_b32 s4, v252, 21
	v_readlane_b32 s5, v252, 22
	v_readlane_b32 s6, v252, 23
	v_readlane_b32 s7, v252, 24
	v_readlane_b32 s26, v252, 25
	v_readlane_b32 s27, v252, 26
	v_readlane_b32 s28, v252, 27
	v_readlane_b32 s29, v252, 28
	v_readlane_b32 s30, v252, 29
	v_readlane_b32 s31, v252, 30
	v_readlane_b32 s33, v252, 31
	v_readlane_b32 s60, v252, 32
	v_readlane_b32 s61, v252, 33
	v_readlane_b32 s62, v252, 34
	s_nop 4
	s_branch .LBB0_730

.LBB0_730:
	s_cmp_lg_u32 s98, 2
	s_cbranch_scc1 .Lmy_b4_go
	s_mov_b32 s98, 3
	v_writelane_b32 v252, s3, 20
	v_writelane_b32 v252, s4, 21
	v_writelane_b32 v252, s5, 22
	v_writelane_b32 v252, s6, 23
	v_writelane_b32 v252, s7, 24
	v_writelane_b32 v252, s26, 25
	v_writelane_b32 v252, s27, 26
	v_writelane_b32 v252, s28, 27
	v_writelane_b32 v252, s29, 28
	v_writelane_b32 v252, s30, 29
	v_writelane_b32 v252, s31, 30
	v_writelane_b32 v252, s33, 31
	v_writelane_b32 v252, s60, 32
	v_writelane_b32 v252, s61, 33
	v_writelane_b32 v252, s62, 34
	v_readlane_b32 s19, v252, 2
	v_readlane_b32 s26, v252, 3
	v_readlane_b32 s27, v252, 4
	v_readlane_b32 s28, v252, 5
	v_readlane_b32 s29, v252, 6
	v_readlane_b32 s30, v252, 7
	v_readlane_b32 s31, v252, 8
	v_readlane_b32 s33, v252, 9
	v_readlane_b32 s38, v252, 10
	v_readlane_b32 s42, v252, 11
	v_readlane_b32 s43, v252, 12
	v_readlane_b32 s44, v252, 13
	v_readlane_b32 s46, v252, 14
	v_readlane_b32 s47, v252, 15
	v_readlane_b32 s49, v252, 16
	v_mbcnt_lo_u32_b32 v196, -1, 0
	s_nop 4
	s_branch .LBB0_629
